# LN_in row reductions: DPP adds and permlane swaps instead of ds_bpermute round trips
# baseline (speedup 1.0000x reference)
; __device__ __forceinline__ float shx(float v, int mask) { return __builtin_bit_cast(float, __builtin_amdgcn_ds_bpermute((lane_now() ^ mask) << 2, __builtin_bit_cast(int, v))); }
; __device__ __forceinline__ unsigned pk4_fp8(float a, float b, float c, float d) { int w = __builtin_amdgcn_cvt_pk_fp8_f32(a, b, 0, false); w = __builtin_amdgcn_cvt_pk_fp8_f32(c, d, w, true); return (unsigned)w; }
; __device__ __forceinline__ float wave_sum(float v) {
; #pragma unroll
;     for (int o = 1; o < 64; o <<= 1) v += shx(v, o);
;     return v;
; }
; __device__ __forceinline__ void ln_rows4(const float* x, const float* g, const float* b, f16* h, unsigned char* h8, int m, int stride, int lane) {
;     f32x4 v[4][4];
; #pragma unroll
;     for (int r = 0; r < 4; ++r)
; #pragma unroll
;         for (int j = 0; j < 4; ++j) v[r][j] = ((const f32x4*)(x + (size_t)(m + r * stride) * DM))[lane + 64 * j];
;     asm volatile("" ::: "memory");
; #pragma unroll
;     for (int r = 0; r < 4; ++r) { float s = 0.f;
; #pragma unroll
;         for (int j = 0; j < 4; ++j) s += (v[r][j].x + v[r][j].y) + (v[r][j].z + v[r][j].w);
;         const float mean = wave_sum(s) * (1.f / DM); float s2 = 0.f;
; #pragma unroll
;         for (int j = 0; j < 4; ++j) { v[r][j] = v[r][j] - mean; s2 += (v[r][j].x * v[r][j].x + v[r][j].y * v[r][j].y) + (v[r][j].z * v[r][j].z + v[r][j].w * v[r][j].w); }
;         const float rstd = 1.f / sqrtf(wave_sum(s2) * (1.f / DM) + LN_EPS);
; #pragma unroll
;         for (int j = 0; j < 4; ++j) { const f32x4 gg = ((const f32x4*)g)[lane + 64 * j], bb = ((const f32x4*)b)[lane + 64 * j]; const f32x4 y = v[r][j] * rstd * gg + bb;
;             u32x2 w; w.x = rd<D_H>(pk_f16(y.x, y.y)); w.y = rd<D_H>(pk_f16(y.z, y.w)); ((u32x2*)(h + (size_t)(m + r * stride) * DM))[lane + 64 * j] = w;
;             ((unsigned*)(h8 + (size_t)(m + r * stride) * DM))[lane + 64 * j] = pk4_fp8(y.x, y.y, y.z, y.w); } }
.LBB0_575:
	v_lshl_add_u64 v[0:1], s[12:13], 0, v[32:33]
	global_load_dwordx4 v[82:85], v[0:1], off
	global_load_dwordx4 v[58:61], v[0:1], off offset:1024
	global_load_dwordx4 v[54:57], v[0:1], off offset:2048
	global_load_dwordx4 v[50:53], v[0:1], off offset:3072
	s_add_i32 s16, s45, s6
	s_ashr_i32 s17, s16, 31
	s_add_i32 s14, s87, s6
	v_lshl_add_u64 v[0:1], s[8:9], 0, v[32:33]
	s_lshl_b64 s[4:5], s[16:17], 12
	s_ashr_i32 s15, s14, 31
	global_load_dwordx4 v[46:49], v[0:1], off
	global_load_dwordx4 v[42:45], v[0:1], off offset:1024
	global_load_dwordx4 v[38:41], v[0:1], off offset:2048
	global_load_dwordx4 v[34:37], v[0:1], off offset:3072
	v_lshl_add_u64 v[0:1], v[66:67], 0, s[4:5]
	s_lshl_b64 s[4:5], s[14:15], 12
	global_load_dwordx4 v[28:31], v[0:1], off
	global_load_dwordx4 v[24:27], v[0:1], off offset:1024
	global_load_dwordx4 v[20:23], v[0:1], off offset:2048
	global_load_dwordx4 v[16:19], v[0:1], off offset:3072
	v_lshl_add_u64 v[0:1], v[66:67], 0, s[4:5]
	global_load_dwordx4 v[12:15], v[0:1], off
	global_load_dwordx4 v[8:11], v[0:1], off offset:1024
	global_load_dwordx4 v[4:7], v[0:1], off offset:2048
	s_nop 0
	global_load_dwordx4 v[0:3], v[0:1], off offset:3072
	s_add_i32 s6, s6, s36
	s_waitcnt vmcnt(0)
	v_mov_b32_e32 v86, v83
	v_mov_b32_e32 v87, v84
	v_mov_b32_e32 v88, v82
	v_mov_b32_e32 v89, v85
	v_pk_add_f32 v[86:87], v[86:87], v[88:89]
	v_mov_b32_e32 v88, v59
	v_mov_b32_e32 v89, v60
	v_mov_b32_e32 v90, v58
	v_mov_b32_e32 v91, v61
	v_pk_add_f32 v[88:89], v[88:89], v[90:91]
	v_add_f32_e32 v86, v86, v87
	v_pk_add_f32 v[88:89], v[88:89], v[88:89] op_sel:[0,1] op_sel_hi:[1,0]
	v_add_f32_e32 v86, 0, v86
	v_add_f32_e32 v90, v54, v55
	v_add_f32_e32 v92, v56, v57
	v_mov_b32_e32 v87, v50
	v_mov_b32_e32 v89, v51
	v_mov_b32_e32 v91, v52
	v_mov_b32_e32 v93, v53
	v_pk_add_f32 v[86:87], v[86:87], v[88:89]
	v_pk_add_f32 v[88:89], v[90:91], v[92:93]
	s_nop 0
	v_pk_add_f32 v[86:87], v[86:87], v[88:89]
	s_nop 0
	v_add_f32_e32 v86, v86, v87
	s_nop 1
	v_add_f32_dpp v86, v86, v86 quad_perm:[1,0,3,2] row_mask:0xf bank_mask:0xf
	s_nop 1
	v_add_f32_dpp v86, v86, v86 quad_perm:[2,3,0,1] row_mask:0xf bank_mask:0xf
	s_nop 1
	v_add_f32_dpp v86, v86, v86 row_half_mirror row_mask:0xf bank_mask:0xf
	s_nop 1
	v_add_f32_dpp v86, v86, v86 row_mirror row_mask:0xf bank_mask:0xf
	v_mov_b32_e32 v87, v86
	s_nop 1
	v_permlane16_swap_b32 v87, v86
	s_nop 0
	v_add_f32_e32 v86, v86, v87
	v_mov_b32_e32 v87, v86
	v_mov_b32_e32 v128, v86
	s_nop 1
	v_permlane32_swap_b32 v87, v128
	s_nop 0
	v_add_f32_e32 v92, v128, v87
	v_fmamk_f32 v95, v92, 0xba800000, v83
	v_fmamk_f32 v94, v92, 0xba800000, v82
	v_fmamk_f32 v85, v92, 0xba800000, v85
	v_fmac_f32_e32 v84, 0xba800000, v92
	v_pk_mul_f32 v[82:83], v[84:85], v[84:85]
	v_pk_mul_f32 v[86:87], v[94:95], v[94:95]
	v_fmamk_f32 v61, v92, 0xba800000, v61
	v_pk_mov_b32 v[88:89], v[86:87], v[82:83] op_sel:[1,0]
	v_mov_b32_e32 v87, v83
	v_pk_add_f32 v[82:83], v[88:89], v[86:87]
	v_fmac_f32_e32 v60, 0xba800000, v92
	v_pk_add_f32 v[86:87], v[82:83], v[82:83] op_sel_hi:[0,1]
	v_fmamk_f32 v83, v92, 0xba800000, v59
	v_fmamk_f32 v82, v92, 0xba800000, v58
	v_pk_mul_f32 v[58:59], v[60:61], v[60:61]
	v_pk_mul_f32 v[88:89], v[82:83], v[82:83]
	v_fmac_f32_e32 v56, 0xba800000, v92
	v_pk_mov_b32 v[90:91], v[88:89], v[58:59] op_sel:[1,0]
	v_mov_b32_e32 v89, v59
	v_pk_add_f32 v[58:59], v[90:91], v[88:89]
	v_fmamk_f32 v57, v92, 0xba800000, v57
	v_pk_add_f32 v[88:89], v[58:59], v[58:59] op_sel_hi:[0,1]
	v_fmamk_f32 v58, v92, 0xba800000, v54
	v_fmamk_f32 v59, v92, 0xba800000, v55
	v_mul_f32_e32 v54, v58, v58
	v_pk_fma_f32 v[54:55], v[58:59], v[58:59], v[54:55] op_sel_hi:[1,1,0]
	v_fmamk_f32 v53, v92, 0xba800000, v53
	v_mul_f32_e32 v54, v56, v56
	v_pk_fma_f32 v[90:91], v[56:57], v[56:57], v[54:55] op_sel_hi:[1,1,0]
	v_fmamk_f32 v52, v92, 0xba800000, v52
	v_fmamk_f32 v51, v92, 0xba800000, v51
	v_fmac_f32_e32 v50, 0xba800000, v92
	v_mul_f32_e32 v54, v50, v50
	v_mul_f32_e32 v90, v51, v51
	v_mul_f32_e32 v86, v52, v52
	v_mul_f32_e32 v88, v53, v53
	v_pk_add_f32 v[54:55], v[54:55], v[90:91]
	v_pk_add_f32 v[86:87], v[86:87], v[88:89]
	s_nop 0
	v_pk_add_f32 v[54:55], v[54:55], v[86:87]
	s_nop 0
	v_add_f32_e32 v54, v54, v55
	s_nop 1
	v_add_f32_dpp v54, v54, v54 quad_perm:[1,0,3,2] row_mask:0xf bank_mask:0xf
	s_nop 1
	v_add_f32_dpp v54, v54, v54 quad_perm:[2,3,0,1] row_mask:0xf bank_mask:0xf
	s_nop 1
	v_add_f32_dpp v54, v54, v54 row_half_mirror row_mask:0xf bank_mask:0xf
	s_nop 1
	v_add_f32_dpp v54, v54, v54 row_mirror row_mask:0xf bank_mask:0xf
	v_mov_b32_e32 v55, v54
	s_nop 1
	v_permlane16_swap_b32 v55, v54
	s_nop 0
	v_add_f32_e32 v54, v54, v55
	v_mov_b32_e32 v55, v54
	s_nop 1
	v_permlane32_swap_b32 v55, v54
	s_nop 0
	v_add_f32_e32 v54, v54, v55
	v_fmamk_f32 v54, v54, 0x3a800000, v223
	v_cmp_gt_f32_e32 vcc, s7, v54
	v_mul_f32_e32 v55, 0x4f800000, v54
	s_nop 0
	v_cndmask_b32_e32 v54, v54, v55, vcc
	v_sqrt_f32_e32 v55, v54
	s_nop 0
	v_add_u32_e32 v86, -1, v55
	v_fma_f32 v87, -v86, v55, v54
	v_cmp_ge_f32_e64 s[4:5], 0, v87
	v_add_u32_e32 v87, 1, v55
	s_nop 0
	v_cndmask_b32_e64 v86, v55, v86, s[4:5]
	v_fma_f32 v55, -v87, v55, v54
	v_cmp_lt_f32_e64 s[4:5], 0, v55
	s_nop 1
	v_cndmask_b32_e64 v55, v86, v87, s[4:5]
	v_mul_f32_e32 v86, 0x37800000, v55
	v_cndmask_b32_e32 v55, v55, v86, vcc
	v_cmp_class_f32_e32 vcc, v54, v224
	s_nop 1
	v_cndmask_b32_e32 v54, v55, v54, vcc
	v_div_scale_f32 v55, s[4:5], v54, v54, 1.0
	v_rcp_f32_e32 v86, v55
	s_nop 0
	v_fma_f32 v87, -v55, v86, 1.0
	v_fmac_f32_e32 v86, v87, v86
	v_div_scale_f32 v87, vcc, 1.0, v54, 1.0
	v_mul_f32_e32 v88, v87, v86
	v_fma_f32 v89, -v55, v88, v87
	v_fmac_f32_e32 v88, v89, v86
	v_fma_f32 v55, -v55, v88, v87
; __device__ __forceinline__ unsigned pk4_fp8(float a, float b, float c, float d) { int w = __builtin_amdgcn_cvt_pk_fp8_f32(a, b, 0, false); w = __builtin_amdgcn_cvt_pk_fp8_f32(c, d, w, true); return (unsigned)w; }
; __device__ __forceinline__ void ln_rows4(const float* x, const float* g, const float* b, f16* h, unsigned char* h8, int m, int stride, int lane) {
;     ...
;     for (int r = 0; r < 4; ++r) { float s = 0.f;
; #pragma unroll
;         for (int j = 0; j < 4; ++j) s += (v[r][j].x + v[r][j].y) + (v[r][j].z + v[r][j].w);
;         const float mean = wave_sum(s) * (1.f / DM); float s2 = 0.f;
; #pragma unroll
;         for (int j = 0; j < 4; ++j) { v[r][j] = v[r][j] - mean; s2 += (v[r][j].x * v[r][j].x + v[r][j].y * v[r][j].y) + (v[r][j].z * v[r][j].z + v[r][j].w * v[r][j].w); }
;         const float rstd = 1.f / sqrtf(wave_sum(s2) * (1.f / DM) + LN_EPS);
; #pragma unroll
;         for (int j = 0; j < 4; ++j) { const f32x4 gg = ((const f32x4*)g)[lane + 64 * j], bb = ((const f32x4*)b)[lane + 64 * j]; const f32x4 y = v[r][j] * rstd * gg + bb;
;             u32x2 w; w.x = rd<D_H>(pk_f16(y.x, y.y)); w.y = rd<D_H>(pk_f16(y.z, y.w)); ((u32x2*)(h + (size_t)(m + r * stride) * DM))[lane + 64 * j] = w;
;             ((unsigned*)(h8 + (size_t)(m + r * stride) * DM))[lane + 64 * j] = pk4_fp8(y.x, y.y, y.z, y.w); } }
	v_div_fmas_f32 v55, v55, v86, v88
	v_div_fixup_f32 v54, v55, v54, 1.0
	v_pk_mul_f32 v[94:95], v[94:95], v[54:55] op_sel_hi:[1,0]
	v_pk_mul_f32 v[84:85], v[84:85], v[54:55] op_sel_hi:[1,0]
	v_pk_fma_f32 v[86:87], v[96:97], v[94:95], v[112:113]
	s_nop 0
	v_cvt_pk_f16_f32 v55, v86, v87
	v_pk_fma_f32 v[84:85], v[98:99], v[84:85], v[114:115]
	v_add_u32_e32 v55, 0x20002, v55
	v_and_b32_e32 v88, 0xfffcfffc, v55
	v_cvt_pk_f16_f32 v55, v84, v85
	v_add_u32_e32 v55, 0x20002, v55
	v_and_b32_e32 v89, 0xfffcfffc, v55
	v_mov_b32_e32 v55, v33
	v_cvt_pk_fp8_f32 v55, v86, v87
	v_lshl_add_u64 v[90:91], s[54:55], 0, v[76:77]
	v_add_co_u32_e32 v94, vcc, s11, v90
	v_cvt_pk_fp8_f32 v55, v84, v85 op_sel:[0,0,1]
	s_nop 0
	v_addc_co_u32_e32 v95, vcc, 0, v91, vcc
	v_lshl_add_u64 v[84:85], s[54:55], 0, v[74:75]
	v_add_co_u32_e32 v84, vcc, s18, v84
	global_store_dwordx2 v[94:95], v[88:89], off
	s_nop 0
	v_addc_co_u32_e32 v85, vcc, 0, v85, vcc
	global_store_dword v[84:85], v55, off
	v_pk_mul_f32 v[82:83], v[82:83], v[54:55] op_sel_hi:[1,0]
	v_pk_mul_f32 v[60:61], v[60:61], v[54:55] op_sel_hi:[1,0]
	v_lshl_add_u64 v[74:75], v[74:75], 0, s[80:81]
	v_lshl_add_u64 v[76:77], v[76:77], 0, s[74:75]
	v_pk_fma_f32 v[82:83], v[100:101], v[82:83], v[116:117]
	s_nop 0
	v_cvt_pk_f16_f32 v55, v82, v83
	v_pk_fma_f32 v[60:61], v[102:103], v[60:61], v[118:119]
	v_add_u32_e32 v55, 0x20002, v55
	v_and_b32_e32 v86, 0xfffcfffc, v55
	v_cvt_pk_f16_f32 v55, v60, v61
	v_add_u32_e32 v55, 0x20002, v55
	v_and_b32_e32 v87, 0xfffcfffc, v55
	v_mov_b32_e32 v55, v33
	v_cvt_pk_fp8_f32 v55, v82, v83
	global_store_dwordx2 v[94:95], v[86:87], off offset:512
	v_cvt_pk_fp8_f32 v55, v60, v61 op_sel:[0,0,1]
	global_store_dword v[84:85], v55, off offset:256
	v_pk_mul_f32 v[58:59], v[58:59], v[54:55] op_sel_hi:[1,0]
	v_pk_mul_f32 v[56:57], v[56:57], v[54:55] op_sel_hi:[1,0]
	v_pk_fma_f32 v[58:59], v[104:105], v[58:59], v[120:121]
	s_nop 0
	v_cvt_pk_f16_f32 v55, v58, v59
	v_pk_fma_f32 v[56:57], v[106:107], v[56:57], v[122:123]
	v_add_u32_e32 v55, 0x20002, v55
	v_and_b32_e32 v60, 0xfffcfffc, v55
	v_cvt_pk_f16_f32 v55, v56, v57
	v_add_u32_e32 v55, 0x20002, v55
	v_and_b32_e32 v61, 0xfffcfffc, v55
	v_mov_b32_e32 v55, v33
	v_cvt_pk_fp8_f32 v55, v58, v59
	global_store_dwordx2 v[94:95], v[60:61], off offset:1024
	v_cvt_pk_fp8_f32 v55, v56, v57 op_sel:[0,0,1]
	global_store_dword v[84:85], v55, off offset:512
	v_pk_mul_f32 v[50:51], v[50:51], v[54:55] op_sel_hi:[1,0]
	v_pk_mul_f32 v[52:53], v[52:53], v[54:55] op_sel_hi:[1,0]
	v_pk_fma_f32 v[50:51], v[50:51], v[108:109], v[124:125]
	v_pk_fma_f32 v[52:53], v[52:53], v[110:111], v[126:127]
	v_cvt_pk_f16_f32 v54, v50, v51
	v_cvt_pk_f16_f32 v55, v52, v53
	v_add_u32_e32 v54, 0x20002, v54
	v_add_u32_e32 v55, 0x20002, v55
	v_and_b32_e32 v54, 0xfffcfffc, v54
	v_and_b32_e32 v55, 0xfffcfffc, v55
	global_store_dwordx2 v[94:95], v[54:55], off offset:1536
	v_mov_b32_e32 v54, v33
	v_cvt_pk_fp8_f32 v54, v50, v51
	v_mov_b32_e32 v50, v47
	v_mov_b32_e32 v51, v48
	v_mov_b32_e32 v55, v45
	v_cvt_pk_fp8_f32 v54, v52, v53 op_sel:[0,0,1]
	v_mov_b32_e32 v52, v46
	v_mov_b32_e32 v53, v49
	v_pk_add_f32 v[50:51], v[50:51], v[52:53]
	global_store_dword v[84:85], v54, off offset:768
	v_mov_b32_e32 v52, v43
	v_mov_b32_e32 v53, v44
	v_mov_b32_e32 v54, v42
	v_pk_add_f32 v[52:53], v[52:53], v[54:55]
	v_add_f32_e32 v50, v50, v51
	v_pk_add_f32 v[52:53], v[52:53], v[52:53] op_sel:[0,1] op_sel_hi:[1,0]
	v_add_f32_e32 v50, 0, v50
	v_add_f32_e32 v54, v38, v39
	v_add_f32_e32 v56, v40, v41
	v_mov_b32_e32 v51, v34
	v_mov_b32_e32 v53, v35
	v_mov_b32_e32 v55, v36
	v_mov_b32_e32 v57, v37
	v_pk_add_f32 v[50:51], v[50:51], v[52:53]
	v_pk_add_f32 v[52:53], v[54:55], v[56:57]
	s_nop 0
	v_pk_add_f32 v[50:51], v[50:51], v[52:53]
	s_nop 0
	v_add_f32_e32 v50, v50, v51
	s_nop 1
	v_add_f32_dpp v50, v50, v50 quad_perm:[1,0,3,2] row_mask:0xf bank_mask:0xf
	s_nop 1
	v_add_f32_dpp v50, v50, v50 quad_perm:[2,3,0,1] row_mask:0xf bank_mask:0xf
	s_nop 1
	v_add_f32_dpp v50, v50, v50 row_half_mirror row_mask:0xf bank_mask:0xf
	s_nop 1
	v_add_f32_dpp v50, v50, v50 row_mirror row_mask:0xf bank_mask:0xf
	v_mov_b32_e32 v51, v50
	s_nop 1
	v_permlane16_swap_b32 v51, v50
	s_nop 0
	v_add_f32_e32 v50, v50, v51
	v_mov_b32_e32 v51, v50
	v_mov_b32_e32 v128, v50
	s_nop 1
	v_permlane32_swap_b32 v51, v128
	s_nop 0
	v_add_f32_e32 v56, v128, v51
	v_fmamk_f32 v59, v56, 0xba800000, v47
	v_fmamk_f32 v58, v56, 0xba800000, v46
	v_fmamk_f32 v49, v56, 0xba800000, v49
	v_fmac_f32_e32 v48, 0xba800000, v56
	v_pk_mul_f32 v[46:47], v[48:49], v[48:49]
	v_pk_mul_f32 v[50:51], v[58:59], v[58:59]
	v_fmamk_f32 v45, v56, 0xba800000, v45
	v_pk_mov_b32 v[52:53], v[50:51], v[46:47] op_sel:[1,0]
	v_mov_b32_e32 v51, v47
	v_pk_add_f32 v[46:47], v[52:53], v[50:51]
	v_fmac_f32_e32 v44, 0xba800000, v56
	v_pk_add_f32 v[50:51], v[46:47], v[46:47] op_sel_hi:[0,1]
	v_fmamk_f32 v47, v56, 0xba800000, v43
	v_fmamk_f32 v46, v56, 0xba800000, v42
	v_pk_mul_f32 v[42:43], v[44:45], v[44:45]
	v_pk_mul_f32 v[52:53], v[46:47], v[46:47]
	v_fmac_f32_e32 v40, 0xba800000, v56
	v_pk_mov_b32 v[54:55], v[52:53], v[42:43] op_sel:[1,0]
	v_mov_b32_e32 v53, v43
	v_pk_add_f32 v[42:43], v[54:55], v[52:53]
	v_fmamk_f32 v41, v56, 0xba800000, v41
	v_pk_add_f32 v[52:53], v[42:43], v[42:43] op_sel_hi:[0,1]
	v_fmamk_f32 v42, v56, 0xba800000, v38
	v_fmamk_f32 v43, v56, 0xba800000, v39
	v_mul_f32_e32 v38, v42, v42
	v_pk_fma_f32 v[38:39], v[42:43], v[42:43], v[38:39] op_sel_hi:[1,1,0]
	v_fmamk_f32 v37, v56, 0xba800000, v37
	v_mul_f32_e32 v38, v40, v40
	v_pk_fma_f32 v[54:55], v[40:41], v[40:41], v[38:39] op_sel_hi:[1,1,0]
	v_fmamk_f32 v36, v56, 0xba800000, v36
	v_fmamk_f32 v35, v56, 0xba800000, v35
; __device__ __forceinline__ unsigned pk4_fp8(float a, float b, float c, float d) { int w = __builtin_amdgcn_cvt_pk_fp8_f32(a, b, 0, false); w = __builtin_amdgcn_cvt_pk_fp8_f32(c, d, w, true); return (unsigned)w; }
; __device__ __forceinline__ void ln_rows4(const float* x, const float* g, const float* b, f16* h, unsigned char* h8, int m, int stride, int lane) {
;     ...
;     for (int r = 0; r < 4; ++r) { float s = 0.f;
; #pragma unroll
;         for (int j = 0; j < 4; ++j) s += (v[r][j].x + v[r][j].y) + (v[r][j].z + v[r][j].w);
;         const float mean = wave_sum(s) * (1.f / DM); float s2 = 0.f;
; #pragma unroll
;         for (int j = 0; j < 4; ++j) { v[r][j] = v[r][j] - mean; s2 += (v[r][j].x * v[r][j].x + v[r][j].y * v[r][j].y) + (v[r][j].z * v[r][j].z + v[r][j].w * v[r][j].w); }
;         const float rstd = 1.f / sqrtf(wave_sum(s2) * (1.f / DM) + LN_EPS);
; #pragma unroll
;         for (int j = 0; j < 4; ++j) { const f32x4 gg = ((const f32x4*)g)[lane + 64 * j], bb = ((const f32x4*)b)[lane + 64 * j]; const f32x4 y = v[r][j] * rstd * gg + bb;
;             u32x2 w; w.x = rd<D_H>(pk_f16(y.x, y.y)); w.y = rd<D_H>(pk_f16(y.z, y.w)); ((u32x2*)(h + (size_t)(m + r * stride) * DM))[lane + 64 * j] = w;
;             ((unsigned*)(h8 + (size_t)(m + r * stride) * DM))[lane + 64 * j] = pk4_fp8(y.x, y.y, y.z, y.w); } }
	v_fmac_f32_e32 v34, 0xba800000, v56
	v_mul_f32_e32 v38, v34, v34
	v_mul_f32_e32 v54, v35, v35
	v_mul_f32_e32 v50, v36, v36
	v_mul_f32_e32 v52, v37, v37
	v_pk_add_f32 v[38:39], v[38:39], v[54:55]
	v_pk_add_f32 v[50:51], v[50:51], v[52:53]
	s_nop 0
	v_pk_add_f32 v[38:39], v[38:39], v[50:51]
	s_nop 0
	v_add_f32_e32 v38, v38, v39
	s_nop 1
	v_add_f32_dpp v38, v38, v38 quad_perm:[1,0,3,2] row_mask:0xf bank_mask:0xf
	s_nop 1
	v_add_f32_dpp v38, v38, v38 quad_perm:[2,3,0,1] row_mask:0xf bank_mask:0xf
	s_nop 1
	v_add_f32_dpp v38, v38, v38 row_half_mirror row_mask:0xf bank_mask:0xf
	s_nop 1
	v_add_f32_dpp v38, v38, v38 row_mirror row_mask:0xf bank_mask:0xf
	v_mov_b32_e32 v39, v38
	s_nop 1
	v_permlane16_swap_b32 v39, v38
	s_nop 0
	v_add_f32_e32 v38, v38, v39
	v_mov_b32_e32 v39, v38
	s_nop 1
	v_permlane32_swap_b32 v39, v38
	s_nop 0
	v_add_f32_e32 v38, v38, v39
	v_fmamk_f32 v38, v38, 0x3a800000, v223
	v_cmp_gt_f32_e32 vcc, s7, v38
	v_mul_f32_e32 v39, 0x4f800000, v38
	s_nop 0
	v_cndmask_b32_e32 v38, v38, v39, vcc
	v_sqrt_f32_e32 v39, v38
	s_nop 0
	v_add_u32_e32 v50, -1, v39
	v_fma_f32 v51, -v50, v39, v38
	v_cmp_ge_f32_e64 s[4:5], 0, v51
	v_add_u32_e32 v51, 1, v39
	s_nop 0
	v_cndmask_b32_e64 v50, v39, v50, s[4:5]
	v_fma_f32 v39, -v51, v39, v38
	v_cmp_lt_f32_e64 s[4:5], 0, v39
	s_nop 1
	v_cndmask_b32_e64 v39, v50, v51, s[4:5]
	v_mul_f32_e32 v50, 0x37800000, v39
	v_cndmask_b32_e32 v39, v39, v50, vcc
	v_cmp_class_f32_e32 vcc, v38, v224
	s_nop 1
	v_cndmask_b32_e32 v38, v39, v38, vcc
	v_div_scale_f32 v39, s[4:5], v38, v38, 1.0
	v_rcp_f32_e32 v50, v39
	s_nop 0
	v_fma_f32 v51, -v39, v50, 1.0
	v_fmac_f32_e32 v50, v51, v50
	v_div_scale_f32 v51, vcc, 1.0, v38, 1.0
	v_mul_f32_e32 v52, v51, v50
	v_fma_f32 v53, -v39, v52, v51
	v_fmac_f32_e32 v52, v53, v50
	v_fma_f32 v39, -v39, v52, v51
	v_div_fmas_f32 v39, v39, v50, v52
	v_div_fixup_f32 v38, v39, v38, 1.0
	v_pk_mul_f32 v[58:59], v[58:59], v[38:39] op_sel_hi:[1,0]
	v_pk_mul_f32 v[48:49], v[48:49], v[38:39] op_sel_hi:[1,0]
	v_pk_fma_f32 v[50:51], v[96:97], v[58:59], v[112:113]
	s_nop 0
	v_cvt_pk_f16_f32 v39, v50, v51
	v_pk_fma_f32 v[48:49], v[98:99], v[48:49], v[114:115]
	v_add_u32_e32 v39, 0x20002, v39
	v_and_b32_e32 v52, 0xfffcfffc, v39
	v_cvt_pk_f16_f32 v39, v48, v49
	v_add_u32_e32 v39, 0x20002, v39
	v_and_b32_e32 v53, 0xfffcfffc, v39
	v_mov_b32_e32 v39, v33
	v_cvt_pk_fp8_f32 v39, v50, v51
	v_lshl_add_u64 v[54:55], s[54:55], 0, v[80:81]
	v_add_co_u32_e32 v58, vcc, s11, v54
	v_cvt_pk_fp8_f32 v39, v48, v49 op_sel:[0,0,1]
	s_nop 0
	v_addc_co_u32_e32 v59, vcc, 0, v55, vcc
	v_lshl_add_u64 v[48:49], s[54:55], 0, v[78:79]
	v_add_co_u32_e32 v48, vcc, s18, v48
	global_store_dwordx2 v[58:59], v[52:53], off
	s_nop 0
	v_addc_co_u32_e32 v49, vcc, 0, v49, vcc
	global_store_dword v[48:49], v39, off
	v_pk_mul_f32 v[46:47], v[46:47], v[38:39] op_sel_hi:[1,0]
	v_pk_mul_f32 v[44:45], v[44:45], v[38:39] op_sel_hi:[1,0]
	v_lshl_add_u64 v[78:79], v[78:79], 0, s[80:81]
	v_lshl_add_u64 v[80:81], v[80:81], 0, s[74:75]
	v_pk_fma_f32 v[46:47], v[100:101], v[46:47], v[116:117]
	s_nop 0
	v_cvt_pk_f16_f32 v39, v46, v47
	v_pk_fma_f32 v[44:45], v[102:103], v[44:45], v[118:119]
	v_add_u32_e32 v39, 0x20002, v39
	v_and_b32_e32 v50, 0xfffcfffc, v39
	v_cvt_pk_f16_f32 v39, v44, v45
	v_add_u32_e32 v39, 0x20002, v39
	v_and_b32_e32 v51, 0xfffcfffc, v39
	v_mov_b32_e32 v39, v33
	v_cvt_pk_fp8_f32 v39, v46, v47
	global_store_dwordx2 v[58:59], v[50:51], off offset:512
	v_cvt_pk_fp8_f32 v39, v44, v45 op_sel:[0,0,1]
	global_store_dword v[48:49], v39, off offset:256
	v_pk_mul_f32 v[42:43], v[42:43], v[38:39] op_sel_hi:[1,0]
	v_pk_mul_f32 v[40:41], v[40:41], v[38:39] op_sel_hi:[1,0]
	v_pk_fma_f32 v[42:43], v[104:105], v[42:43], v[120:121]
	s_nop 0
	v_cvt_pk_f16_f32 v39, v42, v43
	v_pk_fma_f32 v[40:41], v[106:107], v[40:41], v[122:123]
	v_add_u32_e32 v39, 0x20002, v39
	v_and_b32_e32 v44, 0xfffcfffc, v39
	v_cvt_pk_f16_f32 v39, v40, v41
	v_add_u32_e32 v39, 0x20002, v39
	v_and_b32_e32 v45, 0xfffcfffc, v39
	v_mov_b32_e32 v39, v33
	v_cvt_pk_fp8_f32 v39, v42, v43
	global_store_dwordx2 v[58:59], v[44:45], off offset:1024
	v_cvt_pk_fp8_f32 v39, v40, v41 op_sel:[0,0,1]
	global_store_dword v[48:49], v39, off offset:512
	v_pk_mul_f32 v[34:35], v[34:35], v[38:39] op_sel_hi:[1,0]
	v_pk_mul_f32 v[36:37], v[36:37], v[38:39] op_sel_hi:[1,0]
	v_pk_fma_f32 v[34:35], v[34:35], v[108:109], v[124:125]
	v_pk_fma_f32 v[36:37], v[36:37], v[110:111], v[126:127]
	v_cvt_pk_f16_f32 v38, v34, v35
	v_cvt_pk_f16_f32 v39, v36, v37
	v_add_u32_e32 v38, 0x20002, v38
	v_add_u32_e32 v39, 0x20002, v39
	v_and_b32_e32 v38, 0xfffcfffc, v38
	v_and_b32_e32 v39, 0xfffcfffc, v39
	global_store_dwordx2 v[58:59], v[38:39], off offset:1536
	v_mov_b32_e32 v38, v33
	v_cvt_pk_fp8_f32 v38, v34, v35
	v_mov_b32_e32 v34, v29
	v_mov_b32_e32 v35, v30
	v_mov_b32_e32 v39, v27
	v_cvt_pk_fp8_f32 v38, v36, v37 op_sel:[0,0,1]
	v_mov_b32_e32 v36, v28
	v_mov_b32_e32 v37, v31
	v_pk_add_f32 v[34:35], v[34:35], v[36:37]
	global_store_dword v[48:49], v38, off offset:768
	v_mov_b32_e32 v36, v25
	v_mov_b32_e32 v37, v26
	v_mov_b32_e32 v38, v24
	v_pk_add_f32 v[36:37], v[36:37], v[38:39]
	v_add_f32_e32 v34, v34, v35
	v_pk_add_f32 v[36:37], v[36:37], v[36:37] op_sel:[0,1] op_sel_hi:[1,0]
	v_add_f32_e32 v34, 0, v34
	v_add_f32_e32 v38, v20, v21
	v_add_f32_e32 v40, v22, v23
	v_mov_b32_e32 v35, v16
	v_mov_b32_e32 v37, v17
	v_mov_b32_e32 v39, v18
	v_mov_b32_e32 v41, v19
	v_pk_add_f32 v[34:35], v[34:35], v[36:37]
	v_pk_add_f32 v[36:37], v[38:39], v[40:41]
	s_nop 0
	v_pk_add_f32 v[34:35], v[34:35], v[36:37]
	s_nop 0
	v_add_f32_e32 v34, v34, v35
	s_nop 1
	v_add_f32_dpp v34, v34, v34 quad_perm:[1,0,3,2] row_mask:0xf bank_mask:0xf
	s_nop 1
; __device__ __forceinline__ unsigned pk4_fp8(float a, float b, float c, float d) { int w = __builtin_amdgcn_cvt_pk_fp8_f32(a, b, 0, false); w = __builtin_amdgcn_cvt_pk_fp8_f32(c, d, w, true); return (unsigned)w; }
; __device__ __forceinline__ void ln_rows4(const float* x, const float* g, const float* b, f16* h, unsigned char* h8, int m, int stride, int lane) {
;     ...
;     for (int r = 0; r < 4; ++r) { float s = 0.f;
; #pragma unroll
;         for (int j = 0; j < 4; ++j) s += (v[r][j].x + v[r][j].y) + (v[r][j].z + v[r][j].w);
;         const float mean = wave_sum(s) * (1.f / DM); float s2 = 0.f;
; #pragma unroll
;         for (int j = 0; j < 4; ++j) { v[r][j] = v[r][j] - mean; s2 += (v[r][j].x * v[r][j].x + v[r][j].y * v[r][j].y) + (v[r][j].z * v[r][j].z + v[r][j].w * v[r][j].w); }
;         const float rstd = 1.f / sqrtf(wave_sum(s2) * (1.f / DM) + LN_EPS);
; #pragma unroll
;         for (int j = 0; j < 4; ++j) { const f32x4 gg = ((const f32x4*)g)[lane + 64 * j], bb = ((const f32x4*)b)[lane + 64 * j]; const f32x4 y = v[r][j] * rstd * gg + bb;
;             u32x2 w; w.x = rd<D_H>(pk_f16(y.x, y.y)); w.y = rd<D_H>(pk_f16(y.z, y.w)); ((u32x2*)(h + (size_t)(m + r * stride) * DM))[lane + 64 * j] = w;
;             ((unsigned*)(h8 + (size_t)(m + r * stride) * DM))[lane + 64 * j] = pk4_fp8(y.x, y.y, y.z, y.w); } }
	v_add_f32_dpp v34, v34, v34 quad_perm:[2,3,0,1] row_mask:0xf bank_mask:0xf
	s_nop 1
	v_add_f32_dpp v34, v34, v34 row_half_mirror row_mask:0xf bank_mask:0xf
	s_nop 1
	v_add_f32_dpp v34, v34, v34 row_mirror row_mask:0xf bank_mask:0xf
	v_mov_b32_e32 v35, v34
	s_nop 1
	v_permlane16_swap_b32 v35, v34
	s_nop 0
	v_add_f32_e32 v34, v34, v35
	v_mov_b32_e32 v35, v34
	v_mov_b32_e32 v128, v34
	s_nop 1
	v_permlane32_swap_b32 v35, v128
	s_nop 0
	v_add_f32_e32 v40, v128, v35
	v_fmamk_f32 v45, v40, 0xba800000, v29
	v_fmamk_f32 v44, v40, 0xba800000, v28
	v_fmamk_f32 v31, v40, 0xba800000, v31
	v_fmac_f32_e32 v30, 0xba800000, v40
	v_pk_mul_f32 v[28:29], v[30:31], v[30:31]
	v_pk_mul_f32 v[34:35], v[44:45], v[44:45]
	v_fmamk_f32 v27, v40, 0xba800000, v27
	v_pk_mov_b32 v[36:37], v[34:35], v[28:29] op_sel:[1,0]
	v_mov_b32_e32 v35, v29
	v_pk_add_f32 v[28:29], v[36:37], v[34:35]
	v_fmamk_f32 v35, v40, 0xba800000, v25
	v_fmamk_f32 v34, v40, 0xba800000, v24
	v_fmac_f32_e32 v26, 0xba800000, v40
	v_pk_add_f32 v[36:37], v[28:29], v[28:29] op_sel_hi:[0,1]
	v_pk_mul_f32 v[24:25], v[26:27], v[26:27]
	v_pk_mul_f32 v[28:29], v[34:35], v[34:35]
	v_fmac_f32_e32 v22, 0xba800000, v40
	v_pk_mov_b32 v[38:39], v[28:29], v[24:25] op_sel:[1,0]
	v_mov_b32_e32 v29, v25
	v_pk_add_f32 v[24:25], v[38:39], v[28:29]
	v_fmamk_f32 v28, v40, 0xba800000, v20
	v_fmamk_f32 v29, v40, 0xba800000, v21
	v_mul_f32_e32 v20, v28, v28
	v_pk_fma_f32 v[20:21], v[28:29], v[28:29], v[20:21] op_sel_hi:[1,1,0]
	v_fmamk_f32 v23, v40, 0xba800000, v23
	v_mul_f32_e32 v20, v22, v22
	v_pk_add_f32 v[24:25], v[24:25], v[24:25] op_sel_hi:[0,1]
	v_pk_fma_f32 v[38:39], v[22:23], v[22:23], v[20:21] op_sel_hi:[1,1,0]
	v_fmamk_f32 v19, v40, 0xba800000, v19
	v_fmamk_f32 v18, v40, 0xba800000, v18
	v_fmamk_f32 v17, v40, 0xba800000, v17
	v_fmac_f32_e32 v16, 0xba800000, v40
	v_mul_f32_e32 v20, v16, v16
	v_mul_f32_e32 v38, v17, v17
	v_mul_f32_e32 v36, v18, v18
	v_mul_f32_e32 v24, v19, v19
	v_pk_add_f32 v[20:21], v[20:21], v[38:39]
	v_pk_add_f32 v[24:25], v[36:37], v[24:25]
	s_nop 0
	v_pk_add_f32 v[20:21], v[20:21], v[24:25]
	s_nop 0
	v_add_f32_e32 v20, v20, v21
	s_nop 1
	v_add_f32_dpp v20, v20, v20 quad_perm:[1,0,3,2] row_mask:0xf bank_mask:0xf
	s_nop 1
	v_add_f32_dpp v20, v20, v20 quad_perm:[2,3,0,1] row_mask:0xf bank_mask:0xf
	s_nop 1
	v_add_f32_dpp v20, v20, v20 row_half_mirror row_mask:0xf bank_mask:0xf
	s_nop 1
	v_add_f32_dpp v20, v20, v20 row_mirror row_mask:0xf bank_mask:0xf
	v_mov_b32_e32 v21, v20
	s_nop 1
	v_permlane16_swap_b32 v21, v20
	s_nop 0
	v_add_f32_e32 v20, v20, v21
	v_mov_b32_e32 v21, v20
	s_nop 1
	v_permlane32_swap_b32 v21, v20
	s_nop 0
	v_add_f32_e32 v20, v20, v21
	v_fmamk_f32 v20, v20, 0x3a800000, v223
	v_cmp_gt_f32_e32 vcc, s7, v20
	v_mul_f32_e32 v21, 0x4f800000, v20
	s_nop 0
	v_cndmask_b32_e32 v20, v20, v21, vcc
	v_sqrt_f32_e32 v21, v20
	s_nop 0
	v_add_u32_e32 v24, -1, v21
	v_fma_f32 v25, -v24, v21, v20
	v_cmp_ge_f32_e64 s[4:5], 0, v25
	v_add_u32_e32 v25, 1, v21
	s_nop 0
	v_cndmask_b32_e64 v24, v21, v24, s[4:5]
	v_fma_f32 v21, -v25, v21, v20
	v_cmp_lt_f32_e64 s[4:5], 0, v21
	s_nop 1
	v_cndmask_b32_e64 v21, v24, v25, s[4:5]
	v_mul_f32_e32 v24, 0x37800000, v21
	v_cndmask_b32_e32 v21, v21, v24, vcc
	v_cmp_class_f32_e32 vcc, v20, v224
	s_nop 1
	v_cndmask_b32_e32 v20, v21, v20, vcc
	v_div_scale_f32 v21, s[4:5], v20, v20, 1.0
	v_rcp_f32_e32 v24, v21
	s_lshl_b64 s[4:5], s[16:17], 10
	s_lshl_b64 s[16:17], s[16:17], 11
	v_fma_f32 v25, -v21, v24, 1.0
	v_fmac_f32_e32 v24, v25, v24
	v_div_scale_f32 v25, vcc, 1.0, v20, 1.0
	v_mul_f32_e32 v36, v25, v24
	v_fma_f32 v37, -v21, v36, v25
	v_fmac_f32_e32 v36, v37, v24
	v_fma_f32 v21, -v21, v36, v25
	v_div_fmas_f32 v21, v21, v24, v36
	v_div_fixup_f32 v20, v21, v20, 1.0
	v_pk_mul_f32 v[24:25], v[44:45], v[20:21] op_sel_hi:[1,0]
	v_pk_mul_f32 v[30:31], v[30:31], v[20:21] op_sel_hi:[1,0]
	v_pk_fma_f32 v[36:37], v[96:97], v[24:25], v[112:113]
	s_nop 0
	v_cvt_pk_f16_f32 v21, v36, v37
	v_pk_fma_f32 v[30:31], v[98:99], v[30:31], v[114:115]
	v_add_u32_e32 v21, 0x20002, v21
	v_and_b32_e32 v38, 0xfffcfffc, v21
	v_cvt_pk_f16_f32 v21, v30, v31
	v_add_u32_e32 v21, 0x20002, v21
	v_and_b32_e32 v39, 0xfffcfffc, v21
	v_mov_b32_e32 v21, v33
	v_cvt_pk_fp8_f32 v21, v36, v37
	v_lshl_add_u64 v[24:25], v[68:69], 0, s[16:17]
	global_store_dwordx2 v[24:25], v[38:39], off
	v_cvt_pk_fp8_f32 v21, v30, v31 op_sel:[0,0,1]
	v_lshl_add_u64 v[30:31], v[72:73], 0, s[4:5]
	global_store_dword v[30:31], v21, off
	v_pk_mul_f32 v[34:35], v[34:35], v[20:21] op_sel_hi:[1,0]
	v_pk_mul_f32 v[26:27], v[26:27], v[20:21] op_sel_hi:[1,0]
	v_pk_fma_f32 v[34:35], v[100:101], v[34:35], v[116:117]
	s_nop 0
	v_cvt_pk_f16_f32 v21, v34, v35
	v_pk_fma_f32 v[26:27], v[102:103], v[26:27], v[118:119]
	v_add_u32_e32 v21, 0x20002, v21
	v_and_b32_e32 v36, 0xfffcfffc, v21
	v_cvt_pk_f16_f32 v21, v26, v27
	v_add_u32_e32 v21, 0x20002, v21
	v_and_b32_e32 v37, 0xfffcfffc, v21
	v_mov_b32_e32 v21, v33
	v_cvt_pk_fp8_f32 v21, v34, v35
	global_store_dwordx2 v[24:25], v[36:37], off offset:512
	v_cvt_pk_fp8_f32 v21, v26, v27 op_sel:[0,0,1]
	global_store_dword v[30:31], v21, off offset:256
	v_pk_mul_f32 v[26:27], v[28:29], v[20:21] op_sel_hi:[1,0]
	v_pk_mul_f32 v[22:23], v[22:23], v[20:21] op_sel_hi:[1,0]
	v_pk_fma_f32 v[26:27], v[104:105], v[26:27], v[120:121]
	s_nop 0
	v_cvt_pk_f16_f32 v21, v26, v27
	v_pk_fma_f32 v[22:23], v[106:107], v[22:23], v[122:123]
	v_add_u32_e32 v21, 0x20002, v21
	v_and_b32_e32 v28, 0xfffcfffc, v21
	v_cvt_pk_f16_f32 v21, v22, v23
	v_add_u32_e32 v21, 0x20002, v21
	v_and_b32_e32 v29, 0xfffcfffc, v21
	v_mov_b32_e32 v21, v33
	v_cvt_pk_fp8_f32 v21, v26, v27
	global_store_dwordx2 v[24:25], v[28:29], off offset:1024
; __device__ __forceinline__ float shx(float v, int mask) { return __builtin_bit_cast(float, __builtin_amdgcn_ds_bpermute((lane_now() ^ mask) << 2, __builtin_bit_cast(int, v))); }
; __device__ __forceinline__ float wave_sum(float v) {
; #pragma unroll
;     for (int o = 1; o < 64; o <<= 1) v += shx(v, o);
;     return v;
; }
; __device__ __forceinline__ void ln_rows4(const float* x, const float* g, const float* b, f16* h, unsigned char* h8, int m, int stride, int lane) {
;     ...
;     for (int r = 0; r < 4; ++r) { float s = 0.f;
; #pragma unroll
;         for (int j = 0; j < 4; ++j) s += (v[r][j].x + v[r][j].y) + (v[r][j].z + v[r][j].w);
;         const float mean = wave_sum(s) * (1.f / DM); float s2 = 0.f;
; #pragma unroll
;         for (int j = 0; j < 4; ++j) { v[r][j] = v[r][j] - mean; s2 += (v[r][j].x * v[r][j].x + v[r][j].y * v[r][j].y) + (v[r][j].z * v[r][j].z + v[r][j].w * v[r][j].w); }
	v_cvt_pk_fp8_f32 v21, v22, v23 op_sel:[0,0,1]
	v_add_f32_e32 v22, v6, v7
	v_mov_b32_e32 v23, v3
	global_store_dword v[30:31], v21, off offset:512
	v_pk_mul_f32 v[16:17], v[16:17], v[20:21] op_sel_hi:[1,0]
	v_pk_mul_f32 v[18:19], v[18:19], v[20:21] op_sel_hi:[1,0]
	v_pk_fma_f32 v[16:17], v[16:17], v[108:109], v[124:125]
	v_pk_fma_f32 v[18:19], v[18:19], v[110:111], v[126:127]
	v_cvt_pk_f16_f32 v20, v16, v17
	v_cvt_pk_f16_f32 v21, v18, v19
	v_add_u32_e32 v20, 0x20002, v20
	v_add_u32_e32 v21, 0x20002, v21
	v_and_b32_e32 v20, 0xfffcfffc, v20
	v_and_b32_e32 v21, 0xfffcfffc, v21
	global_store_dwordx2 v[24:25], v[20:21], off offset:1536
	v_mov_b32_e32 v20, v33
	v_cvt_pk_fp8_f32 v20, v16, v17
	v_mov_b32_e32 v16, v13
	v_mov_b32_e32 v17, v14
	v_mov_b32_e32 v21, v11
	v_cvt_pk_fp8_f32 v20, v18, v19 op_sel:[0,0,1]
	v_mov_b32_e32 v18, v12
	v_mov_b32_e32 v19, v15
	v_pk_add_f32 v[16:17], v[16:17], v[18:19]
	global_store_dword v[30:31], v20, off offset:768
	v_mov_b32_e32 v18, v9
	v_mov_b32_e32 v19, v10
	v_mov_b32_e32 v20, v8
	v_pk_add_f32 v[18:19], v[18:19], v[20:21]
	v_add_f32_e32 v16, v16, v17
	v_pk_add_f32 v[18:19], v[18:19], v[18:19] op_sel:[0,1] op_sel_hi:[1,0]
	v_add_f32_e32 v16, 0, v16
	v_add_f32_e32 v20, v4, v5
	v_mov_b32_e32 v17, v0
	v_mov_b32_e32 v19, v1
	v_mov_b32_e32 v21, v2
	v_pk_add_f32 v[16:17], v[16:17], v[18:19]
	v_pk_add_f32 v[18:19], v[20:21], v[22:23]
	s_nop 0
	v_pk_add_f32 v[16:17], v[16:17], v[18:19]
	s_nop 0
	v_add_f32_e32 v16, v16, v17
	s_nop 1
	v_add_f32_dpp v16, v16, v16 quad_perm:[1,0,3,2] row_mask:0xf bank_mask:0xf
	s_nop 1
	v_add_f32_dpp v16, v16, v16 quad_perm:[2,3,0,1] row_mask:0xf bank_mask:0xf
	s_nop 1
	v_add_f32_dpp v16, v16, v16 row_half_mirror row_mask:0xf bank_mask:0xf
	s_nop 1
	v_add_f32_dpp v16, v16, v16 row_mirror row_mask:0xf bank_mask:0xf
	v_mov_b32_e32 v17, v16
	s_nop 1
	v_permlane16_swap_b32 v17, v16
	s_nop 0
	v_add_f32_e32 v16, v16, v17
	v_mov_b32_e32 v17, v16
	v_mov_b32_e32 v128, v16
	s_nop 1
	v_permlane32_swap_b32 v17, v128
	s_nop 0
	v_add_f32_e32 v22, v128, v17
	v_fmamk_f32 v27, v22, 0xba800000, v13
	v_fmamk_f32 v26, v22, 0xba800000, v12
	v_fmamk_f32 v15, v22, 0xba800000, v15
	v_fmac_f32_e32 v14, 0xba800000, v22
	v_pk_mul_f32 v[12:13], v[14:15], v[14:15]
	v_pk_mul_f32 v[16:17], v[26:27], v[26:27]
	v_fmamk_f32 v11, v22, 0xba800000, v11
	v_pk_mov_b32 v[18:19], v[16:17], v[12:13] op_sel:[1,0]
	v_mov_b32_e32 v17, v13
	v_pk_add_f32 v[12:13], v[18:19], v[16:17]
	v_fmamk_f32 v17, v22, 0xba800000, v9
	v_fmamk_f32 v16, v22, 0xba800000, v8
	v_fmac_f32_e32 v10, 0xba800000, v22
	v_pk_add_f32 v[18:19], v[12:13], v[12:13] op_sel_hi:[0,1]
	v_pk_mul_f32 v[8:9], v[10:11], v[10:11]
	v_pk_mul_f32 v[12:13], v[16:17], v[16:17]
	v_fmac_f32_e32 v6, 0xba800000, v22
	v_pk_mov_b32 v[20:21], v[12:13], v[8:9] op_sel:[1,0]
	v_mov_b32_e32 v13, v9
	v_pk_add_f32 v[8:9], v[20:21], v[12:13]
	v_fmamk_f32 v12, v22, 0xba800000, v4
	v_fmamk_f32 v13, v22, 0xba800000, v5
	v_mul_f32_e32 v4, v12, v12
	v_pk_fma_f32 v[4:5], v[12:13], v[12:13], v[4:5] op_sel_hi:[1,1,0]
	v_fmamk_f32 v7, v22, 0xba800000, v7
	v_mul_f32_e32 v4, v6, v6
	v_pk_add_f32 v[8:9], v[8:9], v[8:9] op_sel_hi:[0,1]
	v_pk_fma_f32 v[20:21], v[6:7], v[6:7], v[4:5] op_sel_hi:[1,1,0]
	v_fmamk_f32 v3, v22, 0xba800000, v3
	v_fmamk_f32 v2, v22, 0xba800000, v2
	v_fmamk_f32 v1, v22, 0xba800000, v1
	v_fmac_f32_e32 v0, 0xba800000, v22
	v_mul_f32_e32 v4, v0, v0
	v_mul_f32_e32 v20, v1, v1
	v_mul_f32_e32 v18, v2, v2
	v_mul_f32_e32 v8, v3, v3
	v_pk_add_f32 v[4:5], v[4:5], v[20:21]
	v_pk_add_f32 v[8:9], v[18:19], v[8:9]
	s_nop 0
	v_pk_add_f32 v[4:5], v[4:5], v[8:9]
	s_nop 0
	v_add_f32_e32 v4, v4, v5
	s_nop 1
	v_add_f32_dpp v4, v4, v4 quad_perm:[1,0,3,2] row_mask:0xf bank_mask:0xf
	s_nop 1
	v_add_f32_dpp v4, v4, v4 quad_perm:[2,3,0,1] row_mask:0xf bank_mask:0xf
	s_nop 1
	v_add_f32_dpp v4, v4, v4 row_half_mirror row_mask:0xf bank_mask:0xf
	s_nop 1
	v_add_f32_dpp v4, v4, v4 row_mirror row_mask:0xf bank_mask:0xf
; __device__ __forceinline__ unsigned pk4_fp8(float a, float b, float c, float d) { int w = __builtin_amdgcn_cvt_pk_fp8_f32(a, b, 0, false); w = __builtin_amdgcn_cvt_pk_fp8_f32(c, d, w, true); return (unsigned)w; }
; __device__ __forceinline__ void ln_rows4(const float* x, const float* g, const float* b, f16* h, unsigned char* h8, int m, int stride, int lane) {
;     ...
;         for (int j = 0; j < 4; ++j) { v[r][j] = v[r][j] - mean; s2 += (v[r][j].x * v[r][j].x + v[r][j].y * v[r][j].y) + (v[r][j].z * v[r][j].z + v[r][j].w * v[r][j].w); }
;         const float rstd = 1.f / sqrtf(wave_sum(s2) * (1.f / DM) + LN_EPS);
; #pragma unroll
;         for (int j = 0; j < 4; ++j) { const f32x4 gg = ((const f32x4*)g)[lane + 64 * j], bb = ((const f32x4*)b)[lane + 64 * j]; const f32x4 y = v[r][j] * rstd * gg + bb;
;             u32x2 w; w.x = rd<D_H>(pk_f16(y.x, y.y)); w.y = rd<D_H>(pk_f16(y.z, y.w)); ((u32x2*)(h + (size_t)(m + r * stride) * DM))[lane + 64 * j] = w;
;             ((unsigned*)(h8 + (size_t)(m + r * stride) * DM))[lane + 64 * j] = pk4_fp8(y.x, y.y, y.z, y.w); } }
; __global__ void __launch_bounds__(NTHREADS, 2) mk_fwd(Args args) {
;     ...
;                 for (; m + 3 * NGW < M; m += 4 * NGW) ln_rows4(src, g, b, H16, ws + WS_H8, m, NGW, lane);
	v_mov_b32_e32 v5, v4
	s_nop 1
	v_permlane16_swap_b32 v5, v4
	s_nop 0
	v_add_f32_e32 v4, v4, v5
	v_mov_b32_e32 v5, v4
	s_nop 1
	v_permlane32_swap_b32 v5, v4
	s_nop 0
	v_add_f32_e32 v4, v4, v5
	v_fmamk_f32 v4, v4, 0x3a800000, v223
	v_cmp_gt_f32_e32 vcc, s7, v4
	v_mul_f32_e32 v5, 0x4f800000, v4
	s_nop 0
	v_cndmask_b32_e32 v4, v4, v5, vcc
	v_sqrt_f32_e32 v5, v4
	s_nop 0
	v_add_u32_e32 v8, -1, v5
	v_fma_f32 v9, -v8, v5, v4
	v_cmp_ge_f32_e64 s[4:5], 0, v9
	v_add_u32_e32 v9, 1, v5
	s_nop 0
	v_cndmask_b32_e64 v8, v5, v8, s[4:5]
	v_fma_f32 v5, -v9, v5, v4
	v_cmp_lt_f32_e64 s[4:5], 0, v5
	s_nop 1
	v_cndmask_b32_e64 v5, v8, v9, s[4:5]
	v_mul_f32_e32 v8, 0x37800000, v5
	v_cndmask_b32_e32 v5, v5, v8, vcc
	v_cmp_class_f32_e32 vcc, v4, v224
	s_nop 1
	v_cndmask_b32_e32 v4, v5, v4, vcc
	v_div_scale_f32 v5, s[4:5], v4, v4, 1.0
	v_rcp_f32_e32 v8, v5
	s_lshl_b64 s[4:5], s[14:15], 10
	s_lshl_b64 s[14:15], s[14:15], 11
	v_fma_f32 v9, -v5, v8, 1.0
	v_fmac_f32_e32 v8, v9, v8
	v_div_scale_f32 v9, vcc, 1.0, v4, 1.0
	v_mul_f32_e32 v18, v9, v8
	v_fma_f32 v19, -v5, v18, v9
	v_fmac_f32_e32 v18, v19, v8
	v_fma_f32 v5, -v5, v18, v9
	v_div_fmas_f32 v5, v5, v8, v18
	v_div_fixup_f32 v4, v5, v4, 1.0
	v_pk_mul_f32 v[8:9], v[26:27], v[4:5] op_sel_hi:[1,0]
	v_pk_mul_f32 v[14:15], v[14:15], v[4:5] op_sel_hi:[1,0]
	v_pk_fma_f32 v[18:19], v[96:97], v[8:9], v[112:113]
	s_nop 0
	v_cvt_pk_f16_f32 v5, v18, v19
	v_pk_fma_f32 v[14:15], v[98:99], v[14:15], v[114:115]
	v_add_u32_e32 v5, 0x20002, v5
	v_and_b32_e32 v20, 0xfffcfffc, v5
	v_cvt_pk_f16_f32 v5, v14, v15
	v_add_u32_e32 v5, 0x20002, v5
	v_and_b32_e32 v21, 0xfffcfffc, v5
	v_mov_b32_e32 v5, v33
	v_cvt_pk_fp8_f32 v5, v18, v19
	v_lshl_add_u64 v[8:9], v[68:69], 0, s[14:15]
	global_store_dwordx2 v[8:9], v[20:21], off
	v_cvt_pk_fp8_f32 v5, v14, v15 op_sel:[0,0,1]
	v_lshl_add_u64 v[14:15], v[72:73], 0, s[4:5]
	s_add_i32 s4, s87, s6
	s_add_u32 s8, s8, s68
	global_store_dword v[14:15], v5, off
	v_pk_mul_f32 v[16:17], v[16:17], v[4:5] op_sel_hi:[1,0]
	v_pk_mul_f32 v[10:11], v[10:11], v[4:5] op_sel_hi:[1,0]
	s_addc_u32 s9, s9, s69
	s_add_u32 s12, s12, s68
	s_addc_u32 s13, s13, s69
	s_cmpk_gt_i32 s4, 0x3fff
	v_pk_fma_f32 v[16:17], v[100:101], v[16:17], v[116:117]
	s_nop 0
	v_cvt_pk_f16_f32 v5, v16, v17
	v_pk_fma_f32 v[10:11], v[102:103], v[10:11], v[118:119]
	v_add_u32_e32 v5, 0x20002, v5
	v_and_b32_e32 v18, 0xfffcfffc, v5
	v_cvt_pk_f16_f32 v5, v10, v11
	v_add_u32_e32 v5, 0x20002, v5
	v_and_b32_e32 v19, 0xfffcfffc, v5
	v_mov_b32_e32 v5, v33
	v_cvt_pk_fp8_f32 v5, v16, v17
	global_store_dwordx2 v[8:9], v[18:19], off offset:512
	v_cvt_pk_fp8_f32 v5, v10, v11 op_sel:[0,0,1]
	global_store_dword v[14:15], v5, off offset:256
	v_pk_mul_f32 v[10:11], v[12:13], v[4:5] op_sel_hi:[1,0]
	v_pk_mul_f32 v[6:7], v[6:7], v[4:5] op_sel_hi:[1,0]
	v_pk_fma_f32 v[10:11], v[104:105], v[10:11], v[120:121]
	s_nop 0
	v_cvt_pk_f16_f32 v5, v10, v11
	v_pk_fma_f32 v[6:7], v[106:107], v[6:7], v[122:123]
	v_add_u32_e32 v5, 0x20002, v5
	v_and_b32_e32 v12, 0xfffcfffc, v5
	v_cvt_pk_f16_f32 v5, v6, v7
	v_add_u32_e32 v5, 0x20002, v5
	v_and_b32_e32 v13, 0xfffcfffc, v5
	v_mov_b32_e32 v5, v33
	v_cvt_pk_fp8_f32 v5, v10, v11
	global_store_dwordx2 v[8:9], v[12:13], off offset:1024
	v_cvt_pk_fp8_f32 v5, v6, v7 op_sel:[0,0,1]
	global_store_dword v[14:15], v5, off offset:512
	v_pk_mul_f32 v[0:1], v[0:1], v[4:5] op_sel_hi:[1,0]
	v_pk_mul_f32 v[2:3], v[2:3], v[4:5] op_sel_hi:[1,0]
	v_pk_fma_f32 v[0:1], v[0:1], v[108:109], v[124:125]
	v_pk_fma_f32 v[2:3], v[2:3], v[110:111], v[126:127]
	v_cvt_pk_f16_f32 v4, v0, v1
	v_cvt_pk_f16_f32 v5, v2, v3
	v_add_u32_e32 v4, 0x20002, v4
	v_add_u32_e32 v5, 0x20002, v5
	v_and_b32_e32 v4, 0xfffcfffc, v4
	v_and_b32_e32 v5, 0xfffcfffc, v5
	global_store_dwordx2 v[8:9], v[4:5], off offset:1536
	v_mov_b32_e32 v4, v33
	v_cvt_pk_fp8_f32 v4, v0, v1
	v_cvt_pk_fp8_f32 v4, v2, v3 op_sel:[0,0,1]
	global_store_dword v[14:15], v4, off offset:768
	s_cbranch_scc0 .LBB0_575
